# first P4 GEMM epilogue (acc*gate->bf16) de-serialised: gate loads issued 8 steps ahead into dead fragment registers with counted waits
# baseline (speedup 1.0000x reference)
; __device__ __forceinline__ unsigned cvt_pk_bf16(float lo, float hi) { unsigned r; asm volatile("v_cvt_pk_bf16_f32 %0, %1, %2" : "=v"(r) : "v"(lo), "v"(hi)); return r; }
;     __device__ __forceinline__ void operator()(const f32x4 (&acc)[2][2][4][2], const pg8::Unit& u, int wr, int wc, int fr, int fq) const {
;     ...
;                 for (int bj = 0; bj < 2; ++bj) { const size_t off = row * 2048 + col0 + bj * 128; const f32x4 v0 = acc[ai][bj][m][0], v1 = acc[ai][bj][m][1];
;                     float r[8];
;                     if (MODE == 0) { const u32x4 o = *(const u32x4*)(O + off);
;                         r[0] = bflo(o.x) * v0[0]; r[1] = bfhi(o.x) * v0[1]; r[2] = bflo(o.y) * v0[2]; r[3] = bfhi(o.y) * v0[3];
;                         r[4] = bflo(o.z) * v1[0]; r[5] = bfhi(o.z) * v1[1]; r[6] = bflo(o.w) * v1[2]; r[7] = bfhi(o.w) * v1[3]; }
;                     else { const u32x4 gq = *(const u32x4*)(G + off);
;                         r[0] = bflo(gq.x) * v0[0]; r[1] = bfhi(gq.x) * v0[1]; r[2] = bflo(gq.y) * v0[2]; r[3] = bfhi(gq.y) * v0[3];
;                         r[4] = bflo(gq.z) * v1[0]; r[5] = bfhi(gq.z) * v1[1]; r[6] = bflo(gq.w) * v1[2]; r[7] = bfhi(gq.w) * v1[3];
;                         if (MODE == 2) { const u32x4 o = *(const u32x4*)(O + off);
;                             r[0] += bflo(o.x); r[1] += bfhi(o.x); r[2] += bflo(o.y); r[3] += bfhi(o.y); r[4] += bflo(o.z); r[5] += bfhi(o.z); r[6] += bflo(o.w); r[7] += bfhi(o.w); } }
;                     u32x4 w; w.x = cvt_pk_bf16(r[0], r[1]); w.y = cvt_pk_bf16(r[2], r[3]); w.z = cvt_pk_bf16(r[4], r[5]); w.w = cvt_pk_bf16(r[6], r[7]);
;                     *(u32x4*)(O + off) = w; } }
.LBB0_1003:
	v_lshl_add_u32 v148, s68, 8, v155
	v_lshl_or_b32 v146, s80, 8, v160
	v_ashrrev_i32_e32 v149, 31, v148
	v_ashrrev_i32_e32 v147, 31, v146
	v_lshlrev_b64 v[144:145], 11, v[148:149]
	v_lshl_add_u64 v[144:145], v[144:145], 0, v[146:147]
	v_lshlrev_b64 v[144:145], 1, v[144:145]
	v_lshl_add_u64 v[220:221], s[42:43], 0, v[144:145]
	v_lshl_add_u64 v[222:223], s[24:25], 0, v[144:145]
	v_mov_b32_e32 v236, 0x10000
	v_mov_b32_e32 v237, 0
	v_mov_b64_e32 v[224:225], v[220:221]
	v_mov_b64_e32 v[226:227], v[222:223]
	s_andn2_b64 vcc, exec, s[0:1]
	s_mov_b64 s[0:1], -1
	global_load_dwordx4 v[176:179], v[224:225], off
	global_load_dwordx4 v[180:183], v[224:225], off offset:256
	v_lshl_add_u64 v[224:225], v[224:225], 0, v[236:237]
	global_load_dwordx4 v[184:187], v[224:225], off
	global_load_dwordx4 v[190:193], v[224:225], off offset:256
	v_lshl_add_u64 v[224:225], v[224:225], 0, v[236:237]
	global_load_dwordx4 v[194:197], v[224:225], off
	global_load_dwordx4 v[198:201], v[224:225], off offset:256
	v_lshl_add_u64 v[224:225], v[224:225], 0, v[236:237]
	global_load_dwordx4 v[202:205], v[224:225], off
	global_load_dwordx4 v[208:211], v[224:225], off offset:256
	v_lshl_add_u64 v[224:225], v[220:221], 0, s[8:9]
	s_waitcnt vmcnt(7)
	v_lshlrev_b32_e32 v212, 16, v176
	v_and_b32_e32 v213, 0xffff0000, v176
	v_lshlrev_b32_e32 v214, 16, v177
	v_and_b32_e32 v215, 0xffff0000, v177
	v_lshlrev_b32_e32 v216, 16, v178
	v_and_b32_e32 v217, 0xffff0000, v178
	v_lshlrev_b32_e32 v218, 16, v179
	v_and_b32_e32 v219, 0xffff0000, v179
	v_mul_f32_e32 v212, v124, v212
	v_mul_f32_e32 v213, v125, v213
	v_mul_f32_e32 v214, v126, v214
	v_mul_f32_e32 v215, v127, v215
	v_mul_f32_e32 v216, v120, v216
	v_mul_f32_e32 v217, v121, v217
	v_mul_f32_e32 v218, v122, v218
	v_mul_f32_e32 v219, v123, v219
	v_cvt_pk_bf16_f32 v124, v212, v213
	v_cvt_pk_bf16_f32 v125, v214, v215
	v_cvt_pk_bf16_f32 v126, v216, v217
	v_cvt_pk_bf16_f32 v127, v218, v219
	global_store_dwordx4 v[226:227], v[124:127], off
	global_load_dwordx4 v[176:179], v[224:225], off
	s_waitcnt vmcnt(8)
	v_lshlrev_b32_e32 v212, 16, v180
	v_and_b32_e32 v213, 0xffff0000, v180
	v_lshlrev_b32_e32 v214, 16, v181
	v_and_b32_e32 v215, 0xffff0000, v181
	v_lshlrev_b32_e32 v216, 16, v182
	v_and_b32_e32 v217, 0xffff0000, v182
	v_lshlrev_b32_e32 v218, 16, v183
	v_and_b32_e32 v219, 0xffff0000, v183
	v_mul_f32_e32 v212, v116, v212
	v_mul_f32_e32 v213, v117, v213
	v_mul_f32_e32 v214, v118, v214
	v_mul_f32_e32 v215, v119, v215
	v_mul_f32_e32 v216, v112, v216
	v_mul_f32_e32 v217, v113, v217
	v_mul_f32_e32 v218, v114, v218
	v_mul_f32_e32 v219, v115, v219
	v_cvt_pk_bf16_f32 v116, v212, v213
	v_cvt_pk_bf16_f32 v117, v214, v215
	v_cvt_pk_bf16_f32 v118, v216, v217
	v_cvt_pk_bf16_f32 v119, v218, v219
	global_store_dwordx4 v[226:227], v[116:119], off offset:256
	v_lshl_add_u64 v[226:227], v[226:227], 0, v[236:237]
	global_load_dwordx4 v[180:183], v[224:225], off offset:256
	v_lshl_add_u64 v[224:225], v[220:221], 0, s[18:19]
	s_waitcnt vmcnt(9)
	v_lshlrev_b32_e32 v212, 16, v184
	v_and_b32_e32 v213, 0xffff0000, v184
	v_lshlrev_b32_e32 v214, 16, v185
	v_and_b32_e32 v215, 0xffff0000, v185
	v_lshlrev_b32_e32 v216, 16, v186
	v_and_b32_e32 v217, 0xffff0000, v186
	v_lshlrev_b32_e32 v218, 16, v187
	v_and_b32_e32 v219, 0xffff0000, v187
	v_mul_f32_e32 v212, v108, v212
	v_mul_f32_e32 v213, v109, v213
	v_mul_f32_e32 v214, v110, v214
	v_mul_f32_e32 v215, v111, v215
	v_mul_f32_e32 v216, v104, v216
	v_mul_f32_e32 v217, v105, v217
	v_mul_f32_e32 v218, v106, v218
	v_mul_f32_e32 v219, v107, v219
	v_cvt_pk_bf16_f32 v108, v212, v213
	v_cvt_pk_bf16_f32 v109, v214, v215
	v_cvt_pk_bf16_f32 v110, v216, v217
	v_cvt_pk_bf16_f32 v111, v218, v219
	global_store_dwordx4 v[226:227], v[108:111], off
	global_load_dwordx4 v[184:187], v[224:225], off
	s_waitcnt vmcnt(10)
	v_lshlrev_b32_e32 v212, 16, v190
	v_and_b32_e32 v213, 0xffff0000, v190
	v_lshlrev_b32_e32 v214, 16, v191
	v_and_b32_e32 v215, 0xffff0000, v191
	v_lshlrev_b32_e32 v216, 16, v192
	v_and_b32_e32 v217, 0xffff0000, v192
	v_lshlrev_b32_e32 v218, 16, v193
	v_and_b32_e32 v219, 0xffff0000, v193
	v_mul_f32_e32 v212, v100, v212
	v_mul_f32_e32 v213, v101, v213
	v_mul_f32_e32 v214, v102, v214
	v_mul_f32_e32 v215, v103, v215
	v_mul_f32_e32 v216, v96, v216
	v_mul_f32_e32 v217, v97, v217
	v_mul_f32_e32 v218, v98, v218
	v_mul_f32_e32 v219, v99, v219
	v_cvt_pk_bf16_f32 v100, v212, v213
	v_cvt_pk_bf16_f32 v101, v214, v215
	v_cvt_pk_bf16_f32 v102, v216, v217
	v_cvt_pk_bf16_f32 v103, v218, v219
	global_store_dwordx4 v[226:227], v[100:103], off offset:256
	v_lshl_add_u64 v[226:227], v[226:227], 0, v[236:237]
	global_load_dwordx4 v[190:193], v[224:225], off offset:256
	v_lshl_add_u64 v[224:225], v[220:221], 0, s[22:23]
	s_waitcnt vmcnt(11)
	v_lshlrev_b32_e32 v212, 16, v194
	v_and_b32_e32 v213, 0xffff0000, v194
	v_lshlrev_b32_e32 v214, 16, v195
	v_and_b32_e32 v215, 0xffff0000, v195
	v_lshlrev_b32_e32 v216, 16, v196
	v_and_b32_e32 v217, 0xffff0000, v196
	v_lshlrev_b32_e32 v218, 16, v197
	v_and_b32_e32 v219, 0xffff0000, v197
	v_mul_f32_e32 v212, v92, v212
	v_mul_f32_e32 v213, v93, v213
	v_mul_f32_e32 v214, v94, v214
	v_mul_f32_e32 v215, v95, v215
	v_mul_f32_e32 v216, v88, v216
	v_mul_f32_e32 v217, v89, v217
	v_mul_f32_e32 v218, v90, v218
	v_mul_f32_e32 v219, v91, v219
	v_cvt_pk_bf16_f32 v92, v212, v213
	v_cvt_pk_bf16_f32 v93, v214, v215
	v_cvt_pk_bf16_f32 v94, v216, v217
	v_cvt_pk_bf16_f32 v95, v218, v219
	global_store_dwordx4 v[226:227], v[92:95], off
	global_load_dwordx4 v[194:197], v[224:225], off
	s_waitcnt vmcnt(12)
; __device__ __forceinline__ unsigned cvt_pk_bf16(float lo, float hi) { unsigned r; asm volatile("v_cvt_pk_bf16_f32 %0, %1, %2" : "=v"(r) : "v"(lo), "v"(hi)); return r; }
;     __device__ __forceinline__ void operator()(const f32x4 (&acc)[2][2][4][2], const pg8::Unit& u, int wr, int wc, int fr, int fq) const {
;     ...
;                 for (int bj = 0; bj < 2; ++bj) { const size_t off = row * 2048 + col0 + bj * 128; const f32x4 v0 = acc[ai][bj][m][0], v1 = acc[ai][bj][m][1];
;                     float r[8];
;                     if (MODE == 0) { const u32x4 o = *(const u32x4*)(O + off);
;                         r[0] = bflo(o.x) * v0[0]; r[1] = bfhi(o.x) * v0[1]; r[2] = bflo(o.y) * v0[2]; r[3] = bfhi(o.y) * v0[3];
;                         r[4] = bflo(o.z) * v1[0]; r[5] = bfhi(o.z) * v1[1]; r[6] = bflo(o.w) * v1[2]; r[7] = bfhi(o.w) * v1[3]; }
;                     else { const u32x4 gq = *(const u32x4*)(G + off);
;                         r[0] = bflo(gq.x) * v0[0]; r[1] = bfhi(gq.x) * v0[1]; r[2] = bflo(gq.y) * v0[2]; r[3] = bfhi(gq.y) * v0[3];
;                         r[4] = bflo(gq.z) * v1[0]; r[5] = bfhi(gq.z) * v1[1]; r[6] = bflo(gq.w) * v1[2]; r[7] = bfhi(gq.w) * v1[3];
;                         if (MODE == 2) { const u32x4 o = *(const u32x4*)(O + off);
;                             r[0] += bflo(o.x); r[1] += bfhi(o.x); r[2] += bflo(o.y); r[3] += bfhi(o.y); r[4] += bflo(o.z); r[5] += bfhi(o.z); r[6] += bflo(o.w); r[7] += bfhi(o.w); } }
;                     u32x4 w; w.x = cvt_pk_bf16(r[0], r[1]); w.y = cvt_pk_bf16(r[2], r[3]); w.z = cvt_pk_bf16(r[4], r[5]); w.w = cvt_pk_bf16(r[6], r[7]);
;                     *(u32x4*)(O + off) = w; } }
	v_lshlrev_b32_e32 v212, 16, v198
	v_and_b32_e32 v213, 0xffff0000, v198
	v_lshlrev_b32_e32 v214, 16, v199
	v_and_b32_e32 v215, 0xffff0000, v199
	v_lshlrev_b32_e32 v216, 16, v200
	v_and_b32_e32 v217, 0xffff0000, v200
	v_lshlrev_b32_e32 v218, 16, v201
	v_and_b32_e32 v219, 0xffff0000, v201
	v_mul_f32_e32 v212, v84, v212
	v_mul_f32_e32 v213, v85, v213
	v_mul_f32_e32 v214, v86, v214
	v_mul_f32_e32 v215, v87, v215
	v_mul_f32_e32 v216, v80, v216
	v_mul_f32_e32 v217, v81, v217
	v_mul_f32_e32 v218, v82, v218
	v_mul_f32_e32 v219, v83, v219
	v_cvt_pk_bf16_f32 v84, v212, v213
	v_cvt_pk_bf16_f32 v85, v214, v215
	v_cvt_pk_bf16_f32 v86, v216, v217
	v_cvt_pk_bf16_f32 v87, v218, v219
	global_store_dwordx4 v[226:227], v[84:87], off offset:256
	v_lshl_add_u64 v[226:227], v[226:227], 0, v[236:237]
	global_load_dwordx4 v[198:201], v[224:225], off offset:256
	v_lshl_add_u64 v[224:225], v[220:221], 0, s[44:45]
	s_waitcnt vmcnt(13)
	v_lshlrev_b32_e32 v212, 16, v202
	v_and_b32_e32 v213, 0xffff0000, v202
	v_lshlrev_b32_e32 v214, 16, v203
	v_and_b32_e32 v215, 0xffff0000, v203
	v_lshlrev_b32_e32 v216, 16, v204
	v_and_b32_e32 v217, 0xffff0000, v204
	v_lshlrev_b32_e32 v218, 16, v205
	v_and_b32_e32 v219, 0xffff0000, v205
	v_mul_f32_e32 v212, v76, v212
	v_mul_f32_e32 v213, v77, v213
	v_mul_f32_e32 v214, v78, v214
	v_mul_f32_e32 v215, v79, v215
	v_mul_f32_e32 v216, v72, v216
	v_mul_f32_e32 v217, v73, v217
	v_mul_f32_e32 v218, v74, v218
	v_mul_f32_e32 v219, v75, v219
	v_cvt_pk_bf16_f32 v76, v212, v213
	v_cvt_pk_bf16_f32 v77, v214, v215
	v_cvt_pk_bf16_f32 v78, v216, v217
	v_cvt_pk_bf16_f32 v79, v218, v219
	global_store_dwordx4 v[226:227], v[76:79], off
	global_load_dwordx4 v[202:205], v[224:225], off
	s_waitcnt vmcnt(14)
	v_lshlrev_b32_e32 v212, 16, v208
	v_and_b32_e32 v213, 0xffff0000, v208
	v_lshlrev_b32_e32 v214, 16, v209
	v_and_b32_e32 v215, 0xffff0000, v209
	v_lshlrev_b32_e32 v216, 16, v210
	v_and_b32_e32 v217, 0xffff0000, v210
	v_lshlrev_b32_e32 v218, 16, v211
	v_and_b32_e32 v219, 0xffff0000, v211
	v_mul_f32_e32 v212, v68, v212
	v_mul_f32_e32 v213, v69, v213
	v_mul_f32_e32 v214, v70, v214
	v_mul_f32_e32 v215, v71, v215
	v_mul_f32_e32 v216, v64, v216
	v_mul_f32_e32 v217, v65, v217
	v_mul_f32_e32 v218, v66, v218
	v_mul_f32_e32 v219, v67, v219
	v_cvt_pk_bf16_f32 v68, v212, v213
	v_cvt_pk_bf16_f32 v69, v214, v215
	v_cvt_pk_bf16_f32 v70, v216, v217
	v_cvt_pk_bf16_f32 v71, v218, v219
	global_store_dwordx4 v[226:227], v[68:71], off offset:256
	v_lshl_add_u64 v[226:227], v[222:223], 0, s[8:9]
	global_load_dwordx4 v[208:211], v[224:225], off offset:256
	s_waitcnt vmcnt(14)
	v_lshlrev_b32_e32 v212, 16, v176
	v_and_b32_e32 v213, 0xffff0000, v176
	v_lshlrev_b32_e32 v214, 16, v177
	v_and_b32_e32 v215, 0xffff0000, v177
	v_lshlrev_b32_e32 v216, 16, v178
	v_and_b32_e32 v217, 0xffff0000, v178
	v_lshlrev_b32_e32 v218, 16, v179
	v_and_b32_e32 v219, 0xffff0000, v179
	v_mul_f32_e32 v212, v60, v212
	v_mul_f32_e32 v213, v61, v213
	v_mul_f32_e32 v214, v62, v214
	v_mul_f32_e32 v215, v63, v215
	v_mul_f32_e32 v216, v56, v216
	v_mul_f32_e32 v217, v57, v217
	v_mul_f32_e32 v218, v58, v218
	v_mul_f32_e32 v219, v59, v219
	v_cvt_pk_bf16_f32 v60, v212, v213
	v_cvt_pk_bf16_f32 v61, v214, v215
	v_cvt_pk_bf16_f32 v62, v216, v217
	v_cvt_pk_bf16_f32 v63, v218, v219
	global_store_dwordx4 v[226:227], v[60:63], off
	s_waitcnt vmcnt(13)
	v_lshlrev_b32_e32 v212, 16, v180
	v_and_b32_e32 v213, 0xffff0000, v180
	v_lshlrev_b32_e32 v214, 16, v181
	v_and_b32_e32 v215, 0xffff0000, v181
	v_lshlrev_b32_e32 v216, 16, v182
	v_and_b32_e32 v217, 0xffff0000, v182
	v_lshlrev_b32_e32 v218, 16, v183
	v_and_b32_e32 v219, 0xffff0000, v183
	v_mul_f32_e32 v212, v52, v212
	v_mul_f32_e32 v213, v53, v213
	v_mul_f32_e32 v214, v54, v214
	v_mul_f32_e32 v215, v55, v215
	v_mul_f32_e32 v216, v48, v216
	v_mul_f32_e32 v217, v49, v217
	v_mul_f32_e32 v218, v50, v218
	v_mul_f32_e32 v219, v51, v219
	v_cvt_pk_bf16_f32 v52, v212, v213
	v_cvt_pk_bf16_f32 v53, v214, v215
	v_cvt_pk_bf16_f32 v54, v216, v217
	v_cvt_pk_bf16_f32 v55, v218, v219
	global_store_dwordx4 v[226:227], v[52:55], off offset:256
	v_lshl_add_u64 v[226:227], v[222:223], 0, s[18:19]
	s_waitcnt vmcnt(12)
; __device__ __forceinline__ unsigned cvt_pk_bf16(float lo, float hi) { unsigned r; asm volatile("v_cvt_pk_bf16_f32 %0, %1, %2" : "=v"(r) : "v"(lo), "v"(hi)); return r; }
;     __device__ __forceinline__ void operator()(const f32x4 (&acc)[2][2][4][2], const pg8::Unit& u, int wr, int wc, int fr, int fq) const {
;     ...
;                 for (int bj = 0; bj < 2; ++bj) { const size_t off = row * 2048 + col0 + bj * 128; const f32x4 v0 = acc[ai][bj][m][0], v1 = acc[ai][bj][m][1];
;                     float r[8];
;                     if (MODE == 0) { const u32x4 o = *(const u32x4*)(O + off);
;                         r[0] = bflo(o.x) * v0[0]; r[1] = bfhi(o.x) * v0[1]; r[2] = bflo(o.y) * v0[2]; r[3] = bfhi(o.y) * v0[3];
;                         r[4] = bflo(o.z) * v1[0]; r[5] = bfhi(o.z) * v1[1]; r[6] = bflo(o.w) * v1[2]; r[7] = bfhi(o.w) * v1[3]; }
;                     else { const u32x4 gq = *(const u32x4*)(G + off);
;                         r[0] = bflo(gq.x) * v0[0]; r[1] = bfhi(gq.x) * v0[1]; r[2] = bflo(gq.y) * v0[2]; r[3] = bfhi(gq.y) * v0[3];
;                         r[4] = bflo(gq.z) * v1[0]; r[5] = bfhi(gq.z) * v1[1]; r[6] = bflo(gq.w) * v1[2]; r[7] = bfhi(gq.w) * v1[3];
;                         if (MODE == 2) { const u32x4 o = *(const u32x4*)(O + off);
;                             r[0] += bflo(o.x); r[1] += bfhi(o.x); r[2] += bflo(o.y); r[3] += bfhi(o.y); r[4] += bflo(o.z); r[5] += bfhi(o.z); r[6] += bflo(o.w); r[7] += bfhi(o.w); } }
;                     u32x4 w; w.x = cvt_pk_bf16(r[0], r[1]); w.y = cvt_pk_bf16(r[2], r[3]); w.z = cvt_pk_bf16(r[4], r[5]); w.w = cvt_pk_bf16(r[6], r[7]);
;                     *(u32x4*)(O + off) = w; } }
	v_lshlrev_b32_e32 v212, 16, v184
	v_and_b32_e32 v213, 0xffff0000, v184
	v_lshlrev_b32_e32 v214, 16, v185
	v_and_b32_e32 v215, 0xffff0000, v185
	v_lshlrev_b32_e32 v216, 16, v186
	v_and_b32_e32 v217, 0xffff0000, v186
	v_lshlrev_b32_e32 v218, 16, v187
	v_and_b32_e32 v219, 0xffff0000, v187
	v_mul_f32_e32 v212, v44, v212
	v_mul_f32_e32 v213, v45, v213
	v_mul_f32_e32 v214, v46, v214
	v_mul_f32_e32 v215, v47, v215
	v_mul_f32_e32 v216, v40, v216
	v_mul_f32_e32 v217, v41, v217
	v_mul_f32_e32 v218, v42, v218
	v_mul_f32_e32 v219, v43, v219
	v_cvt_pk_bf16_f32 v44, v212, v213
	v_cvt_pk_bf16_f32 v45, v214, v215
	v_cvt_pk_bf16_f32 v46, v216, v217
	v_cvt_pk_bf16_f32 v47, v218, v219
	global_store_dwordx4 v[226:227], v[44:47], off
	s_waitcnt vmcnt(11)
	v_lshlrev_b32_e32 v212, 16, v190
	v_and_b32_e32 v213, 0xffff0000, v190
	v_lshlrev_b32_e32 v214, 16, v191
	v_and_b32_e32 v215, 0xffff0000, v191
	v_lshlrev_b32_e32 v216, 16, v192
	v_and_b32_e32 v217, 0xffff0000, v192
	v_lshlrev_b32_e32 v218, 16, v193
	v_and_b32_e32 v219, 0xffff0000, v193
	v_mul_f32_e32 v212, v36, v212
	v_mul_f32_e32 v213, v37, v213
	v_mul_f32_e32 v214, v38, v214
	v_mul_f32_e32 v215, v39, v215
	v_mul_f32_e32 v216, v32, v216
	v_mul_f32_e32 v217, v33, v217
	v_mul_f32_e32 v218, v34, v218
	v_mul_f32_e32 v219, v35, v219
	v_cvt_pk_bf16_f32 v36, v212, v213
	v_cvt_pk_bf16_f32 v37, v214, v215
	v_cvt_pk_bf16_f32 v38, v216, v217
	v_cvt_pk_bf16_f32 v39, v218, v219
	global_store_dwordx4 v[226:227], v[36:39], off offset:256
	v_lshl_add_u64 v[226:227], v[222:223], 0, s[22:23]
	s_waitcnt vmcnt(10)
	v_lshlrev_b32_e32 v212, 16, v194
	v_and_b32_e32 v213, 0xffff0000, v194
	v_lshlrev_b32_e32 v214, 16, v195
	v_and_b32_e32 v215, 0xffff0000, v195
	v_lshlrev_b32_e32 v216, 16, v196
	v_and_b32_e32 v217, 0xffff0000, v196
	v_lshlrev_b32_e32 v218, 16, v197
	v_and_b32_e32 v219, 0xffff0000, v197
	v_mul_f32_e32 v212, v28, v212
	v_mul_f32_e32 v213, v29, v213
	v_mul_f32_e32 v214, v30, v214
	v_mul_f32_e32 v215, v31, v215
	v_mul_f32_e32 v216, v24, v216
	v_mul_f32_e32 v217, v25, v217
	v_mul_f32_e32 v218, v26, v218
	v_mul_f32_e32 v219, v27, v219
	v_cvt_pk_bf16_f32 v28, v212, v213
	v_cvt_pk_bf16_f32 v29, v214, v215
	v_cvt_pk_bf16_f32 v30, v216, v217
	v_cvt_pk_bf16_f32 v31, v218, v219
	global_store_dwordx4 v[226:227], v[28:31], off
	s_waitcnt vmcnt(9)
	v_lshlrev_b32_e32 v212, 16, v198
	v_and_b32_e32 v213, 0xffff0000, v198
	v_lshlrev_b32_e32 v214, 16, v199
	v_and_b32_e32 v215, 0xffff0000, v199
	v_lshlrev_b32_e32 v216, 16, v200
	v_and_b32_e32 v217, 0xffff0000, v200
	v_lshlrev_b32_e32 v218, 16, v201
	v_and_b32_e32 v219, 0xffff0000, v201
	v_mul_f32_e32 v212, v20, v212
	v_mul_f32_e32 v213, v21, v213
	v_mul_f32_e32 v214, v22, v214
	v_mul_f32_e32 v215, v23, v215
	v_mul_f32_e32 v216, v16, v216
	v_mul_f32_e32 v217, v17, v217
	v_mul_f32_e32 v218, v18, v218
	v_mul_f32_e32 v219, v19, v219
	v_cvt_pk_bf16_f32 v20, v212, v213
	v_cvt_pk_bf16_f32 v21, v214, v215
	v_cvt_pk_bf16_f32 v22, v216, v217
	v_cvt_pk_bf16_f32 v23, v218, v219
	global_store_dwordx4 v[226:227], v[20:23], off offset:256
	v_lshl_add_u64 v[226:227], v[222:223], 0, s[44:45]
	s_waitcnt vmcnt(8)
	v_lshlrev_b32_e32 v212, 16, v202
	v_and_b32_e32 v213, 0xffff0000, v202
	v_lshlrev_b32_e32 v214, 16, v203
	v_and_b32_e32 v215, 0xffff0000, v203
	v_lshlrev_b32_e32 v216, 16, v204
	v_and_b32_e32 v217, 0xffff0000, v204
	v_lshlrev_b32_e32 v218, 16, v205
	v_and_b32_e32 v219, 0xffff0000, v205
	v_mul_f32_e32 v212, v12, v212
	v_mul_f32_e32 v213, v13, v213
	v_mul_f32_e32 v214, v14, v214
	v_mul_f32_e32 v215, v15, v215
	v_mul_f32_e32 v216, v8, v216
	v_mul_f32_e32 v217, v9, v217
	v_mul_f32_e32 v218, v10, v218
	v_mul_f32_e32 v219, v11, v219
	v_cvt_pk_bf16_f32 v12, v212, v213
	v_cvt_pk_bf16_f32 v13, v214, v215
	v_cvt_pk_bf16_f32 v14, v216, v217
	v_cvt_pk_bf16_f32 v15, v218, v219
	global_store_dwordx4 v[226:227], v[12:15], off
	s_waitcnt vmcnt(7)
	v_lshlrev_b32_e32 v212, 16, v208
	v_and_b32_e32 v213, 0xffff0000, v208
	v_lshlrev_b32_e32 v214, 16, v209
	v_and_b32_e32 v215, 0xffff0000, v209
	v_lshlrev_b32_e32 v216, 16, v210
	v_and_b32_e32 v217, 0xffff0000, v210
	v_lshlrev_b32_e32 v218, 16, v211
	v_and_b32_e32 v219, 0xffff0000, v211
	v_mul_f32_e32 v212, v4, v212
	v_mul_f32_e32 v213, v5, v213
	v_mul_f32_e32 v214, v6, v214
	v_mul_f32_e32 v215, v7, v215
	v_mul_f32_e32 v216, v0, v216
	v_mul_f32_e32 v217, v1, v217
	v_mul_f32_e32 v218, v2, v218
	v_mul_f32_e32 v219, v3, v219
	v_cvt_pk_bf16_f32 v4, v212, v213
	v_cvt_pk_bf16_f32 v5, v214, v215
	v_cvt_pk_bf16_f32 v6, v216, v217
	v_cvt_pk_bf16_f32 v7, v218, v219
	global_store_dwordx4 v[226:227], v[4:7], off offset:256
	s_nop 0
	s_nop 0
	s_nop 0
	s_nop 0
	s_nop 0
	s_nop 0
	s_nop 0
	s_nop 0
	s_nop 0
	s_nop 0
	s_nop 0
	s_nop 0
	s_cbranch_vccnz .LBB0_992
	s_andn2_b64 vcc, exec, s[10:11]
	s_cbranch_vccnz .LBB0_991
	s_barrier
	s_branch .LBB0_991
